# K-buffer toggle xors moved into the mandatory MFMA-to-VALU wait slot; mask block hazard pad restored
# speedup vs baseline: 1.0080x; 1.0011x over previous
; #define SBAR() __builtin_amdgcn_sched_barrier(0)
; #define QK_RD(d0, sl) do { if ((d0) < 8) { const int a_ = kbase ^ (((d0) & 7) << 5); KRD(f0[sl], a_, 0); KRD(f1[sl], a_, 32 * 256); } \
;                            else { const int a_ = rbase ^ (((d0) & 3) << 5); KRD(f0[sl], a_, 0); KRD(f1[sl], a_, 32 * 128); } } while (0)
; #define LGKM(n) asm volatile("s_waitcnt lgkmcnt(" #n ")" ::: "memory")
; __device__ __forceinline__ void mphase(bool has_pv, f32x16* o, int vb, bf16x8 pa0, bf16x8 pa1, bf16x8 pa2, bf16x8 pa3, f32x16& p0, f32x16& p1, int kbase, int rbase, const bf16x8* qr) {
;     ...
;     QK_RD(0, 0); QK_RD(1, 1);
;     p0 = f32x16{}; p1 = f32x16{};
; #pragma unroll
;     for (int d0 = 0; d0 < 12; ++d0) {
;         if (d0 + 2 < 12) { QK_RD(d0 + 2, (d0 + 2) % 3); LGKM(4); }
;         else if (d0 + 1 < 12) LGKM(2);
;         else LGKM(0);
;         SBAR();
;         p0 = __builtin_amdgcn_mfma_f32_32x32x16_bf16(f0[d0 % 3], qr[d0], p0, 0, 0, 0);
;         p1 = __builtin_amdgcn_mfma_f32_32x32x16_bf16(f1[d0 % 3], qr[d0], p1, 0, 0, 0);
;         SBAR(); }
; __device__ __forceinline__ void attn_block(const Ptrs& P, int b, int h, int qb, LAS char* lds) {
;     ...
;         { const int kb_ = x * KVBLK; if (kb_ + KVBLK - 1 > qlo) { const int dq = qm - kb_; const float NEG = -__builtin_inff();
; #pragma unroll
;             for (int r = 0; r < 16; ++r) { const int c_ = (r & 3) + 8 * (r >> 2); if (dq - c_ < 0) p0[r] = NEG; if (dq - c_ - 32 < 0) p1[r] = NEG; } } }
.Lattn_qk:
	s_waitcnt lgkmcnt(4)
	v_mfma_f32_32x32x16_bf16 v[84:99], v[68:71], v[100:103], v[224:239]
	v_mfma_f32_32x32x16_bf16 v[68:83], v[72:75], v[100:103], v[224:239]
	v_xor_b32_e32 v199, 0x60, v3
	ds_read_b128 v[216:219], v199 offset:0
	ds_read_b128 v[220:223], v199 offset:0x2000
	s_waitcnt lgkmcnt(4)
	v_mfma_f32_32x32x16_bf16 v[84:99], v[200:203], v[104:107], v[84:99]
	v_mfma_f32_32x32x16_bf16 v[68:83], v[204:207], v[104:107], v[68:83]
	v_xor_b32_e32 v199, 0x80, v3
	ds_read_b128 v[200:203], v199 offset:0
	ds_read_b128 v[204:207], v199 offset:0x2000
	s_waitcnt lgkmcnt(4)
	v_mfma_f32_32x32x16_bf16 v[84:99], v[208:211], v[108:111], v[84:99]
	v_mfma_f32_32x32x16_bf16 v[68:83], v[212:215], v[108:111], v[68:83]
	v_xor_b32_e32 v199, 0xa0, v3
	ds_read_b128 v[208:211], v199 offset:0
	ds_read_b128 v[212:215], v199 offset:0x2000
	s_waitcnt lgkmcnt(4)
	v_mfma_f32_32x32x16_bf16 v[84:99], v[216:219], v[112:115], v[84:99]
	v_mfma_f32_32x32x16_bf16 v[68:83], v[220:223], v[112:115], v[68:83]
	v_xor_b32_e32 v199, 0xc0, v3
	ds_read_b128 v[216:219], v199 offset:0
	ds_read_b128 v[220:223], v199 offset:0x2000
	s_waitcnt lgkmcnt(4)
	v_mfma_f32_32x32x16_bf16 v[84:99], v[200:203], v[116:119], v[84:99]
	v_mfma_f32_32x32x16_bf16 v[68:83], v[204:207], v[116:119], v[68:83]
	v_xor_b32_e32 v199, 0xe0, v3
	ds_read_b128 v[200:203], v199 offset:0
	ds_read_b128 v[204:207], v199 offset:0x2000
	s_waitcnt lgkmcnt(4)
	v_mfma_f32_32x32x16_bf16 v[84:99], v[208:211], v[120:123], v[84:99]
	v_mfma_f32_32x32x16_bf16 v[68:83], v[212:215], v[120:123], v[68:83]
	ds_read_b128 v[208:211], v197 offset:0
	ds_read_b128 v[212:215], v197 offset:0x1000
	s_waitcnt lgkmcnt(4)
	v_mfma_f32_32x32x16_bf16 v[84:99], v[216:219], v[124:127], v[84:99]
	v_mfma_f32_32x32x16_bf16 v[68:83], v[220:223], v[124:127], v[68:83]
	v_xor_b32_e32 v199, 32, v197
	ds_read_b128 v[216:219], v199 offset:0
	ds_read_b128 v[220:223], v199 offset:0x1000
	s_waitcnt lgkmcnt(4)
	v_mfma_f32_32x32x16_bf16 v[84:99], v[200:203], v[128:131], v[84:99]
	v_mfma_f32_32x32x16_bf16 v[68:83], v[204:207], v[128:131], v[68:83]
	v_xor_b32_e32 v199, 64, v197
	ds_read_b128 v[200:203], v199 offset:0
	ds_read_b128 v[204:207], v199 offset:0x1000
	s_waitcnt lgkmcnt(4)
	v_mfma_f32_32x32x16_bf16 v[84:99], v[208:211], v[132:135], v[84:99]
	v_mfma_f32_32x32x16_bf16 v[68:83], v[212:215], v[132:135], v[68:83]
	v_xor_b32_e32 v199, 0x60, v197
	ds_read_b128 v[208:211], v199 offset:0
	ds_read_b128 v[212:215], v199 offset:0x1000
	s_waitcnt lgkmcnt(4)
	v_mfma_f32_32x32x16_bf16 v[84:99], v[216:219], v[136:139], v[84:99]
	v_mfma_f32_32x32x16_bf16 v[68:83], v[220:223], v[136:139], v[68:83]
	s_waitcnt lgkmcnt(2)
	v_mfma_f32_32x32x16_bf16 v[84:99], v[200:203], v[140:143], v[84:99]
	v_mfma_f32_32x32x16_bf16 v[68:83], v[204:207], v[140:143], v[68:83]
	s_waitcnt lgkmcnt(0)
	v_mfma_f32_32x32x16_bf16 v[84:99], v[208:211], v[144:147], v[84:99]
	v_mfma_f32_32x32x16_bf16 v[68:83], v[212:215], v[144:147], v[68:83]
	s_setprio 0
	s_cmp_le_u32 s82, s75
	s_barrier
	s_cbranch_scc1 .LBB0_619
	v_add_u32_e32 v199, s81, v195
	s_nop 3
	v_cmp_gt_i32_e64 s[22:23], -16, v199
	v_cmp_gt_i32_e64 s[98:99], 16, v199
	v_cmp_gt_i32_e64 s[100:101], -15, v199
	v_cmp_gt_i32_e64 vcc, 17, v199
	v_cndmask_b32_e64 v84, v84, v191, s[22:23]
	v_cndmask_b32_e64 v68, v68, v191, s[98:99]
	v_cndmask_b32_e64 v85, v85, v191, s[100:101]
	v_cndmask_b32_e64 v69, v69, v191, vcc
	v_cmp_gt_i32_e64 s[22:23], -14, v199
	v_cmp_gt_i32_e64 s[98:99], 18, v199
	v_cmp_gt_i32_e64 s[100:101], -13, v199
	v_cmp_gt_i32_e64 vcc, 19, v199
	v_cndmask_b32_e64 v86, v86, v191, s[22:23]
	v_cndmask_b32_e64 v70, v70, v191, s[98:99]
	v_cndmask_b32_e64 v87, v87, v191, s[100:101]
	v_cndmask_b32_e64 v71, v71, v191, vcc
	v_cmp_gt_i32_e64 s[22:23], -8, v199
	v_cmp_gt_i32_e64 s[98:99], 24, v199
	v_cmp_gt_i32_e64 s[100:101], -7, v199
	v_cmp_gt_i32_e64 vcc, 25, v199
	v_cndmask_b32_e64 v88, v88, v191, s[22:23]
	v_cndmask_b32_e64 v72, v72, v191, s[98:99]
	v_cndmask_b32_e64 v89, v89, v191, s[100:101]
	v_cndmask_b32_e64 v73, v73, v191, vcc
	v_cmp_gt_i32_e64 s[22:23], -6, v199
	v_cmp_gt_i32_e64 s[98:99], 26, v199
	v_cmp_gt_i32_e64 s[100:101], -5, v199
	v_cmp_gt_i32_e64 vcc, 27, v199
	v_cndmask_b32_e64 v90, v90, v191, s[22:23]
	v_cndmask_b32_e64 v74, v74, v191, s[98:99]
	v_cndmask_b32_e64 v91, v91, v191, s[100:101]
	v_cndmask_b32_e64 v75, v75, v191, vcc
	v_cmp_gt_i32_e64 s[22:23], 0, v199
	v_cmp_gt_i32_e64 s[98:99], 32, v199
	v_cmp_gt_i32_e64 s[100:101], 1, v199
	v_cmp_gt_i32_e64 vcc, 33, v199
	v_cndmask_b32_e64 v92, v92, v191, s[22:23]
	v_cndmask_b32_e64 v76, v76, v191, s[98:99]
	v_cndmask_b32_e64 v93, v93, v191, s[100:101]
	v_cndmask_b32_e64 v77, v77, v191, vcc
	v_cmp_gt_i32_e64 s[22:23], 2, v199
	v_cmp_gt_i32_e64 s[98:99], 34, v199
	v_cmp_gt_i32_e64 s[100:101], 3, v199
	v_cmp_gt_i32_e64 vcc, 35, v199
	v_cndmask_b32_e64 v94, v94, v191, s[22:23]
	v_cndmask_b32_e64 v78, v78, v191, s[98:99]
	v_cndmask_b32_e64 v95, v95, v191, s[100:101]
	v_cndmask_b32_e64 v79, v79, v191, vcc
	v_cmp_gt_i32_e64 s[22:23], 8, v199
	v_cmp_gt_i32_e64 s[98:99], 40, v199
	v_cmp_gt_i32_e64 s[100:101], 9, v199
	v_cmp_gt_i32_e64 vcc, 41, v199
	v_cndmask_b32_e64 v96, v96, v191, s[22:23]
	v_cndmask_b32_e64 v80, v80, v191, s[98:99]
	v_cndmask_b32_e64 v97, v97, v191, s[100:101]
	v_cndmask_b32_e64 v81, v81, v191, vcc
	v_cmp_gt_i32_e64 s[22:23], 10, v199
	v_cmp_gt_i32_e64 s[98:99], 42, v199
	v_cmp_gt_i32_e64 s[100:101], 11, v199
	v_cmp_gt_i32_e64 vcc, 43, v199
	v_cndmask_b32_e64 v98, v98, v191, s[22:23]
	v_cndmask_b32_e64 v82, v82, v191, s[98:99]
	v_cndmask_b32_e64 v99, v99, v191, s[100:101]
	v_cndmask_b32_e64 v83, v83, v191, vcc
; __device__ __forceinline__ void attn_block(const Ptrs& P, int b, int h, int qb, LAS char* lds) {
;     ...
;         kbase ^= SHM_K; rbase ^= SHM_R;
;     ...
;         float pmax = p0[0];
; #pragma unroll
;         for (int r = 1; r < 16; ++r) pmax = fmaxf(pmax, p0[r]);
; #pragma unroll
;         for (int r = 0; r < 16; ++r) pmax = fmaxf(pmax, p1[r]);
;         { auto sw_ = __builtin_amdgcn_permlane32_swap(__float_as_uint(pmax), __float_as_uint(pmax), false, false); pmax = fmaxf(__uint_as_float(sw_[0]), __uint_as_float(sw_[1])); }
;         float alpha = 1.f;
;         if (!__all(pmax - m_reg <= THRL)) { const float mn = fmaxf(m_reg, pmax); alpha = __builtin_amdgcn_exp2f(m_reg - mn); m_reg = mn; }
.LBB0_619:
	v_xor_b32_e32 v3, 0x4000, v3
	v_xor_b32_e32 v197, 0x2000, v197
	s_nop 4
	v_max3_f32 v199, v84, v85, v86
	v_max3_f32 v199, v199, v87, v88
	v_max3_f32 v199, v199, v89, v90
	v_max3_f32 v199, v199, v91, v92
	v_max3_f32 v199, v199, v93, v94
	v_max3_f32 v199, v199, v95, v96
	v_max3_f32 v199, v199, v97, v98
	v_max3_f32 v199, v199, v99, v68
	v_max3_f32 v199, v199, v69, v70
	v_max3_f32 v199, v199, v71, v72
	v_max3_f32 v199, v199, v73, v74
	v_max3_f32 v199, v199, v75, v76
	v_max3_f32 v199, v199, v77, v78
	v_max3_f32 v199, v199, v79, v80
	v_max3_f32 v199, v199, v81, v82
	v_max_f32_e32 v199, v199, v83
	v_mov_b32_e32 v200, v199
	s_nop 1
	v_permlane32_swap_b32_e32 v199, v200
	v_max_f32_e32 v199, v199, v200
	v_cmp_ge_f32_e32 vcc, s68, v199
	s_andn2_b64 s[22:23], vcc, s[56:57]
	s_cmp_eq_u64 s[22:23], exec
	s_cbranch_scc1 .Lattn_fast
	v_max_f32_e32 v200, 0, v199
	v_cndmask_b32_e64 v200, v200, v199, s[56:57]
	v_add_f32_e32 v196, v196, v200
	v_sub_f32_e32 v84, v84, v200
	v_sub_f32_e32 v85, v85, v200
	v_sub_f32_e32 v86, v86, v200
	v_sub_f32_e32 v87, v87, v200
	v_sub_f32_e32 v88, v88, v200
	v_sub_f32_e32 v89, v89, v200
	v_sub_f32_e32 v90, v90, v200
	v_sub_f32_e32 v91, v91, v200
	v_sub_f32_e32 v92, v92, v200
	v_sub_f32_e32 v93, v93, v200
	v_sub_f32_e32 v94, v94, v200
	v_sub_f32_e32 v95, v95, v200
	v_sub_f32_e32 v96, v96, v200
	v_sub_f32_e32 v97, v97, v200
	v_sub_f32_e32 v98, v98, v200
	v_sub_f32_e32 v99, v99, v200
	v_sub_f32_e32 v68, v68, v200
	v_sub_f32_e32 v69, v69, v200
	v_sub_f32_e32 v70, v70, v200
	v_sub_f32_e32 v71, v71, v200
	v_sub_f32_e32 v72, v72, v200
	v_sub_f32_e32 v73, v73, v200
	v_sub_f32_e32 v74, v74, v200
	v_sub_f32_e32 v75, v75, v200
	v_sub_f32_e32 v76, v76, v200
	v_sub_f32_e32 v77, v77, v200
	v_sub_f32_e32 v78, v78, v200
	v_sub_f32_e32 v79, v79, v200
	v_sub_f32_e32 v80, v80, v200
	v_sub_f32_e32 v81, v81, v200
	v_sub_f32_e32 v82, v82, v200
	v_sub_f32_e32 v83, v83, v200
	v_sub_f32_e32 v224, v224, v200
	v_sub_f32_e32 v225, v225, v200
	v_sub_f32_e32 v226, v226, v200
	v_sub_f32_e32 v227, v227, v200
	v_sub_f32_e32 v228, v228, v200
	v_sub_f32_e32 v229, v229, v200
	v_sub_f32_e32 v230, v230, v200
	v_sub_f32_e32 v231, v231, v200
	v_sub_f32_e32 v232, v232, v200
	v_sub_f32_e32 v233, v233, v200
	v_sub_f32_e32 v234, v234, v200
	v_sub_f32_e32 v235, v235, v200
	v_sub_f32_e32 v236, v236, v200
	v_sub_f32_e32 v237, v237, v200
	v_sub_f32_e32 v238, v238, v200
	v_sub_f32_e32 v239, v239, v200
	v_sub_f32_e32 v201, 0, v200
	v_exp_f32_e32 v201, v201
	s_nop 0
	v_cndmask_b32_e64 v200, v201, 0, s[56:57]
	s_branch .Lattn_exp

; __device__ __forceinline__ int crow(int r, int hi) { return (r & 3) + 8 * (r >> 2) + 4 * hi; }
; __device__ __forceinline__ void attn_block(const Ptrs& P, int b, int h, int qb, LAS char* lds) {
;     ...
;         mphase(x > 0, o, vb0 + pv3 * SHM_V, pa0, pa1, pa2, pa3, p0, p1, kbase, rbase, qr); if (x > 0) pv3 = pv3 == 2 ? 0 : pv3 + 1;
;         __builtin_amdgcn_s_setprio(0);
;         kbase ^= SHM_K; rbase ^= SHM_R;
;         __syncthreads();
;         { const int kb_ = x * KVBLK; if (kb_ + KVBLK - 1 > qlo) { const int dq = qm - kb_; const float NEG = -__builtin_inff();
; #pragma unroll
;             for (int r = 0; r < 16; ++r) { const int c_ = (r & 3) + 8 * (r >> 2); if (dq - c_ < 0) p0[r] = NEG; if (dq - c_ - 32 < 0) p1[r] = NEG; } } }
;         float pmax = p0[0];
; #pragma unroll
;         for (int r = 1; r < 16; ++r) pmax = fmaxf(pmax, p0[r]);
; #pragma unroll
;         for (int r = 0; r < 16; ++r) pmax = fmaxf(pmax, p1[r]);
;         { auto sw_ = __builtin_amdgcn_permlane32_swap(__float_as_uint(pmax), __float_as_uint(pmax), false, false); pmax = fmaxf(__uint_as_float(sw_[0]), __uint_as_float(sw_[1])); }
;         float alpha = 1.f;
;         if (!__all(pmax - m_reg <= THRL)) { const float mn = fmaxf(m_reg, pmax); alpha = __builtin_amdgcn_exp2f(m_reg - mn); m_reg = mn; }
; #pragma unroll
;         for (int r = 0; r < 16; ++r) { p0[r] = __builtin_amdgcn_exp2f(p0[r] - m_reg); p1[r] = __builtin_amdgcn_exp2f(p1[r] - m_reg); }
;         float ps = 0.f;
; #pragma unroll
;         for (int r = 0; r < 16; ++r) ps += p0[r];
; #pragma unroll
;         for (int r = 0; r < 16; ++r) ps += p1[r];
;         { auto sw_ = __builtin_amdgcn_permlane32_swap(__float_as_uint(ps), __float_as_uint(ps), false, false); ps = __uint_as_float(sw_[0]) + __uint_as_float(sw_[1]); }
;         l_reg = l_reg * alpha + ps;
;         PK4(p0, 0, pa0); PK4(p0, 8, pa1); PK4(p1, 0, pa2); PK4(p1, 8, pa3);
;         if (__any(alpha < 1.f)) { if (hi == 0) al_l[r32] = alpha; asm volatile("s_waitcnt lgkmcnt(0)" ::: "memory");
; #pragma unroll
;             for (int d_ = 0; d_ < 4; ++d_)
; #pragma unroll
;                 for (int r = 0; r < 16; ++r) o[d_][r] *= al_l[crow(r, hi)]; }
;         if (ts < NT) SWRITE(ts, ts3);
;         if (ts + 1 < NT) SLOAD(ts + 1);
;         ++ts; ts3 = ts3 == 2 ? 0 : ts3 + 1;
;         __syncthreads();
.LBB0_627:
	s_add_i32 s22, s83, 1
	s_cmp_lg_u32 s83, 2
	s_cselect_b32 s39, s22, 0
	s_and_b64 s[22:23], exec, s[56:57]
	s_cselect_b32 s83, s83, s39
	s_add_i32 s22, s38, 1
	s_cmp_lg_u32 s38, 2
	s_cselect_b32 s38, s22, 0
	s_sub_i32 s81, s81, 64
	s_addk_i32 s78, 0x2000
	s_addk_i32 s79, 0x4000
	s_add_i32 s22, s80, s81
	s_add_i32 s82, s82, 64
	s_add_i32 s77, s77, 1
	v_add_f32_e32 v198, v198, v85
	s_cmp_eq_u32 s22, 0
	s_waitcnt lgkmcnt(0)
	s_barrier
	s_cbranch_scc1 .LBB0_629
	s_branch .LBB0_615
